# ECONV loop: the wait for the halo row moved below the remaining three row loads (all 8 loads issue back to back; vmcnt(5)->vmcnt(8) at the new position)
# speedup vs baseline: 1.0092x; 1.0076x over previous
.LBB0_51:
	s_or_b64 exec, exec, s[38:39]
	v_add_u32_e32 v26, 2, v127
	v_ashrrev_i32_e32 v27, 31, v26
	v_lshlrev_b64 v[110:111], 11, v[26:27]
	v_lshl_add_u64 v[26:27], v[58:59], 0, v[110:111]
	global_load_dwordx4 v[102:105], v[26:27], off
	v_lshl_add_u64 v[26:27], v[60:61], 0, v[110:111]
	global_load_dwordx4 v[118:121], v[26:27], off
	v_add_u32_e32 v26, 3, v127
	v_ashrrev_i32_e32 v27, 31, v26
	v_lshlrev_b64 v[90:91], 11, v[26:27]
	v_lshl_add_u64 v[26:27], v[58:59], 0, v[90:91]
	global_load_dwordx4 v[46:49], v[26:27], off
	v_lshl_add_u64 v[26:27], v[60:61], 0, v[90:91]
	global_load_dwordx4 v[50:53], v[26:27], off
	v_add_u32_e32 v26, 4, v127
	v_ashrrev_i32_e32 v27, 31, v26
	v_lshlrev_b64 v[92:93], 11, v[26:27]
	v_lshl_add_u64 v[26:27], v[58:59], 0, v[92:93]
	v_lshl_add_u64 v[30:31], v[60:61], 0, v[92:93]
	global_load_dwordx4 v[26:29], v[26:27], off
	global_load_dwordx4 v[42:45], v[30:31], off
	v_add_u32_e32 v30, 5, v127
	v_ashrrev_i32_e32 v31, 31, v30
	v_lshlrev_b64 v[88:89], 11, v[30:31]
	v_lshl_add_u64 v[30:31], v[58:59], 0, v[88:89]
	global_load_dwordx4 v[30:33], v[30:31], off
	v_lshl_add_u64 v[34:35], v[60:61], 0, v[88:89]
	global_load_dwordx4 v[34:37], v[34:35], off
	s_waitcnt vmcnt(8)
	v_lshlrev_b32_e32 v94, 16, v54
	v_and_b32_e32 v96, 0xffff0000, v54
	v_lshlrev_b32_e32 v100, 16, v55
	v_and_b32_e32 v98, 0xffff0000, v55
	v_lshlrev_b32_e32 v54, 16, v56
	v_lshlrev_b32_e32 v106, 16, v57
	v_add_u32_e32 v126, s2, v126
	s_movk_i32 s15, 0x2003
	v_cmp_lt_i32_e32 vcc, s15, v126
	v_add_u32_e32 v127, s6, v127
	s_or_b64 s[42:43], vcc, s[42:43]
	s_waitcnt vmcnt(7)
	v_lshlrev_b32_e32 v95, 16, v102
	v_pk_mul_f32 v[124:125], v[76:77], v[94:95]
	v_and_b32_e32 v97, 0xffff0000, v102
	v_lshlrev_b32_e32 v101, 16, v103
	v_lshlrev_b32_e32 v55, 16, v104
	v_and_b32_e32 v102, 0xffff0000, v56
	v_lshlrev_b32_e32 v107, 16, v105
	v_lshlrev_b32_e32 v56, 16, v38
	s_waitcnt vmcnt(6)
	v_lshlrev_b32_e32 v0, 16, v118
	v_and_b32_e32 v94, 0xffff0000, v118
	v_lshlrev_b32_e32 v130, 16, v119
	v_pk_mul_f32 v[108:109], v[72:73], v[100:101]
	v_and_b32_e32 v100, 0xffff0000, v119
	v_lshlrev_b32_e32 v131, 16, v120
	v_pk_mul_f32 v[114:115], v[68:69], v[54:55]
	v_and_b32_e32 v54, 0xffff0000, v120
	v_lshlrev_b32_e32 v132, 16, v121
	v_pk_mul_f32 v[118:119], v[64:65], v[106:107]
	v_and_b32_e32 v106, 0xffff0000, v121
	v_lshl_add_u64 v[120:121], v[62:63], 0, v[110:111]
	v_fma_f32 v110, v22, v56, v124
	v_and_b32_e32 v99, 0xffff0000, v103
	v_and_b32_e32 v103, 0xffff0000, v104
	v_and_b32_e32 v104, 0xffff0000, v57
	s_waitcnt vmcnt(5)
	v_lshlrev_b32_e32 v57, 16, v46
	v_add_f32_e32 v110, v110, v125
	v_mul_f32_e32 v0, v110, v0
	v_pk_mul_f32 v[110:111], v[76:77], v[56:57]
	v_pk_mul_f32 v[128:129], v[78:79], v[96:97]
	v_fma_f32 v56, v22, v95, v110
	v_and_b32_e32 v110, 0xffff0000, v38
	v_fma_f32 v38, v23, v110, v128
	v_add_f32_e32 v56, v56, v111
	v_and_b32_e32 v111, 0xffff0000, v46
	v_add_f32_e32 v38, v38, v129
	v_mul_f32_e32 v38, v38, v94
	v_pk_mul_f32 v[124:125], v[78:79], v[110:111]
	v_cvt_pk_bf16_f32 v38, v0, v38
	s_waitcnt vmcnt(4)
	v_lshlrev_b32_e32 v133, 16, v50
	v_fma_f32 v0, v23, v97, v124
	v_and_b32_e32 v50, 0xffff0000, v50
	v_add_f32_e32 v0, v0, v125
	v_lshlrev_b32_e32 v124, 16, v39
	v_mul_f32_e32 v0, v0, v50
	v_lshlrev_b32_e32 v125, 16, v47
	v_fma_f32 v50, v24, v124, v108
	v_add_f32_e32 v50, v50, v109
	v_pk_mul_f32 v[108:109], v[72:73], v[124:125]
	v_lshlrev_b32_e32 v46, 16, v51
	v_fma_f32 v94, v24, v101, v108
	v_add_f32_e32 v94, v94, v109
	v_pk_mul_f32 v[112:113], v[74:75], v[98:99]
	v_mul_f32_e32 v94, v94, v46
	v_and_b32_e32 v46, 0xffff0000, v39
	v_fma_f32 v39, v25, v46, v112
	v_add_f32_e32 v39, v39, v113
	v_mul_f32_e32 v50, v50, v130
	v_and_b32_e32 v47, 0xffff0000, v47
	v_mul_f32_e32 v39, v39, v100
	v_and_b32_e32 v108, 0xffff0000, v51
	v_cvt_pk_bf16_f32 v39, v50, v39
	v_pk_mul_f32 v[50:51], v[74:75], v[46:47]
	v_lshlrev_b32_e32 v100, 16, v52
	v_fma_f32 v46, v25, v99, v50
	v_add_f32_e32 v46, v46, v51
	v_lshlrev_b32_e32 v50, 16, v40
	v_mul_f32_e32 v46, v46, v108
	v_fma_f32 v108, v18, v50, v114
	v_lshlrev_b32_e32 v51, 16, v48
	v_add_f32_e32 v108, v108, v115
	v_mul_f32_e32 v110, v108, v131
	v_pk_mul_f32 v[108:109], v[68:69], v[50:51]
	v_and_b32_e32 v52, 0xffff0000, v52
	v_fma_f32 v50, v18, v55, v108
	v_add_f32_e32 v50, v50, v109
	v_and_b32_e32 v109, 0xffff0000, v48
	v_and_b32_e32 v108, 0xffff0000, v40
	v_pk_mul_f32 v[112:113], v[70:71], v[108:109]
	v_mul_f32_e32 v50, v50, v100
	v_fma_f32 v48, v19, v103, v112
	v_add_f32_e32 v48, v48, v113
	v_lshlrev_b32_e32 v112, 16, v41
	v_lshlrev_b32_e32 v113, 16, v49
	v_pk_mul_f32 v[114:115], v[64:65], v[112:113]
	v_pk_mul_f32 v[116:117], v[70:71], v[102:103]
	v_fma_f32 v100, v20, v107, v114
	v_and_b32_e32 v105, 0xffff0000, v105
	v_mul_f32_e32 v52, v48, v52
	v_lshlrev_b32_e32 v48, 16, v53
	v_add_f32_e32 v100, v100, v115
	v_pk_mul_f32 v[122:123], v[66:67], v[104:105]
	v_fma_f32 v40, v19, v108, v116
	v_mul_f32_e32 v100, v100, v48
	v_and_b32_e32 v48, 0xffff0000, v41
	v_add_f32_e32 v40, v40, v117
	v_fma_f32 v41, v21, v48, v122
	v_mul_f32_e32 v40, v40, v54
	v_fma_f32 v54, v20, v112, v118
	v_add_f32_e32 v41, v41, v123
	v_add_f32_e32 v54, v54, v119
	v_and_b32_e32 v49, 0xffff0000, v49
	v_mul_f32_e32 v41, v41, v106
	v_cvt_pk_bf16_f32 v40, v110, v40
	v_mul_f32_e32 v54, v54, v132
	v_cvt_pk_bf16_f32 v41, v54, v41
	global_store_dwordx4 v[120:121], v[38:41], off
	v_and_b32_e32 v53, 0xffff0000, v53
	v_mul_f32_e32 v56, v56, v133
	v_pk_mul_f32 v[38:39], v[66:67], v[48:49]
	v_cvt_pk_bf16_f32 v40, v50, v52
	s_waitcnt vmcnt(3)
	v_lshlrev_b32_e32 v48, 16, v43
	v_fma_f32 v38, v21, v105, v38
	v_add_f32_e32 v38, v38, v39
	v_mul_f32_e32 v41, v38, v53
	v_cvt_pk_bf16_f32 v41, v100, v41
	v_lshl_add_u64 v[52:53], v[62:63], 0, v[90:91]
	v_cvt_pk_bf16_f32 v38, v56, v0
	v_cvt_pk_bf16_f32 v39, v94, v46
	global_store_dwordx4 v[52:53], v[38:41], off
	v_lshlrev_b32_e32 v0, 16, v42
	v_and_b32_e32 v46, 0xffff0000, v42
	v_lshlrev_b32_e32 v40, 16, v26
	s_waitcnt vmcnt(3)
	v_lshlrev_b32_e32 v41, 16, v30
	v_and_b32_e32 v50, 0xffff0000, v43
	v_pk_mov_b32 v[42:43], v[94:95], v[40:41] op_sel:[1,0]
	v_pk_mul_f32 v[40:41], v[86:87], v[40:41]
	v_pk_mul_f32 v[42:43], v[76:77], v[42:43]
	v_fma_f32 v40, v6, v57, v40
	s_waitcnt vmcnt(2)
	v_lshlrev_b32_e32 v54, 16, v34
	v_fma_f32 v42, v22, v57, v42
	v_add_f32_e32 v40, v40, v41
	v_add_f32_e32 v42, v42, v43
	v_mul_f32_e32 v54, v40, v54
	v_and_b32_e32 v41, 0xffff0000, v30
	v_and_b32_e32 v40, 0xffff0000, v26
	v_mul_f32_e32 v0, v42, v0
	v_pk_mov_b32 v[42:43], v[96:97], v[40:41] op_sel:[1,0]
	v_pk_mul_f32 v[40:41], v[14:15], v[40:41]
	v_pk_mul_f32 v[42:43], v[78:79], v[42:43]
	v_and_b32_e32 v34, 0xffff0000, v34
	v_fma_f32 v26, v23, v111, v42
	v_add_f32_e32 v26, v26, v43
	v_mul_f32_e32 v26, v26, v46
	v_cvt_pk_bf16_f32 v26, v0, v26
	v_fma_f32 v0, v7, v111, v40
	v_add_f32_e32 v0, v0, v41
	v_lshlrev_b32_e32 v40, 16, v27
	v_lshlrev_b32_e32 v41, 16, v31
	v_pk_mov_b32 v[42:43], v[100:101], v[40:41] op_sel:[1,0]
	v_mul_f32_e32 v0, v0, v34
	v_pk_mul_f32 v[42:43], v[72:73], v[42:43]
	v_pk_mul_f32 v[40:41], v[84:85], v[40:41]
	v_fma_f32 v34, v24, v125, v42
	v_add_f32_e32 v34, v34, v43
	v_mul_f32_e32 v42, v34, v48
	v_fma_f32 v34, v8, v125, v40
	v_lshlrev_b32_e32 v30, 16, v35
	v_add_f32_e32 v34, v34, v41
	v_mul_f32_e32 v40, v34, v30
	v_and_b32_e32 v31, 0xffff0000, v31
	v_and_b32_e32 v30, 0xffff0000, v27
	v_and_b32_e32 v41, 0xffff0000, v35
	v_pk_mov_b32 v[34:35], v[98:99], v[30:31] op_sel:[1,0]
	v_pk_mul_f32 v[30:31], v[16:17], v[30:31]
	v_pk_mul_f32 v[34:35], v[74:75], v[34:35]
	v_fma_f32 v30, v9, v47, v30
	v_add_f32_e32 v30, v30, v31
	v_fma_f32 v27, v25, v47, v34
	v_mul_f32_e32 v41, v30, v41
	v_lshlrev_b32_e32 v30, 16, v28
	v_lshlrev_b32_e32 v31, 16, v32
	v_add_f32_e32 v27, v27, v35
	v_pk_mov_b32 v[34:35], v[54:55], v[30:31] op_sel:[1,0]
	v_pk_mul_f32 v[30:31], v[82:83], v[30:31]
	v_mul_f32_e32 v27, v27, v50
	v_pk_mul_f32 v[34:35], v[68:69], v[34:35]
	v_fma_f32 v30, v2, v51, v30
	v_cvt_pk_bf16_f32 v27, v42, v27
	v_lshlrev_b32_e32 v42, 16, v36
	v_fma_f32 v34, v18, v51, v34
	v_add_f32_e32 v30, v30, v31
	v_lshlrev_b32_e32 v52, 16, v44
	v_add_f32_e32 v34, v34, v35
	v_mul_f32_e32 v42, v30, v42
	v_and_b32_e32 v31, 0xffff0000, v32
	v_and_b32_e32 v30, 0xffff0000, v28
	v_mul_f32_e32 v43, v34, v52
	v_pk_mov_b32 v[34:35], v[102:103], v[30:31] op_sel:[1,0]
	v_pk_mul_f32 v[30:31], v[10:11], v[30:31]
	v_and_b32_e32 v36, 0xffff0000, v36
	v_fma_f32 v30, v3, v109, v30
	v_pk_mul_f32 v[34:35], v[70:71], v[34:35]
	v_add_f32_e32 v30, v30, v31
	v_fma_f32 v28, v19, v109, v34
	v_mul_f32_e32 v36, v30, v36
	v_lshlrev_b32_e32 v30, 16, v29
	v_lshlrev_b32_e32 v31, 16, v33
	v_add_f32_e32 v28, v28, v35
	v_pk_mov_b32 v[34:35], v[106:107], v[30:31] op_sel:[1,0]
	v_pk_mul_f32 v[30:31], v[80:81], v[30:31]
	v_pk_mul_f32 v[34:35], v[64:65], v[34:35]
	v_fma_f32 v30, v4, v113, v30
	v_lshlrev_b32_e32 v32, 16, v37
	v_fma_f32 v34, v20, v113, v34
	v_add_f32_e32 v30, v30, v31
	v_add_f32_e32 v34, v34, v35
	v_mul_f32_e32 v35, v30, v32
	v_and_b32_e32 v31, 0xffff0000, v33
	v_and_b32_e32 v30, 0xffff0000, v29
	v_pk_mov_b32 v[32:33], v[104:105], v[30:31] op_sel:[1,0]
	v_and_b32_e32 v44, 0xffff0000, v44
	v_pk_mul_f32 v[32:33], v[66:67], v[32:33]
	v_lshlrev_b32_e32 v53, 16, v45
	v_fma_f32 v29, v21, v49, v32
	v_and_b32_e32 v45, 0xffff0000, v45
	v_add_f32_e32 v29, v29, v33
	v_lshl_add_u64 v[38:39], v[62:63], 0, v[92:93]
	v_mul_f32_e32 v28, v28, v44
	v_mul_f32_e32 v29, v29, v45
	v_cvt_pk_bf16_f32 v28, v43, v28
	v_mul_f32_e32 v34, v34, v53
	v_cvt_pk_bf16_f32 v29, v34, v29
	global_store_dwordx4 v[38:39], v[26:29], off
	v_and_b32_e32 v37, 0xffff0000, v37
	s_nop 0
	v_pk_mul_f32 v[26:27], v[12:13], v[30:31]
	v_lshl_add_u64 v[30:31], v[62:63], 0, v[88:89]
	v_fma_f32 v26, v5, v49, v26
	v_add_f32_e32 v26, v26, v27
	v_mul_f32_e32 v29, v26, v37
	v_cvt_pk_bf16_f32 v26, v54, v0
	v_cvt_pk_bf16_f32 v27, v40, v41
	v_cvt_pk_bf16_f32 v28, v42, v36
	v_cvt_pk_bf16_f32 v29, v35, v29
	global_store_dwordx4 v[30:31], v[26:29], off
	s_andn2_b64 exec, exec, s[42:43]
	s_cbranch_execz .LBB0_64
